# v17 + combine prologue: the 16 serialized load/wait/ds_write trips staging the GLU weights issued as 16 loads, one wait, 16 LDS writes
# speedup vs baseline: 1.0126x; 1.0071x over previous
.LBB0_319:
	v_ashrrev_i32_e32 v76, 5, v186
	v_lshlrev_b32_e32 v78, 9, v76
	v_mov_b32_e32 v79, 0
	v_lshl_add_u64 v[72:73], v[4:5], 0, v[78:79]
	v_mad_u32_u24 v74, v76, s14, v6
	v_add_u32_e32 v75, 0x10800, v74
	global_load_dwordx4 v[8:11], v[72:73], off
	v_add_co_u32_e32 v72, vcc, 0x2000, v72
	v_addc_co_u32_e32 v73, vcc, 0, v73, vcc
	global_load_dwordx4 v[12:15], v[72:73], off
	v_add_co_u32_e32 v72, vcc, 0x2000, v72
	v_addc_co_u32_e32 v73, vcc, 0, v73, vcc
	global_load_dwordx4 v[16:19], v[72:73], off
	v_add_co_u32_e32 v72, vcc, 0x2000, v72
	v_addc_co_u32_e32 v73, vcc, 0, v73, vcc
	global_load_dwordx4 v[20:23], v[72:73], off
	v_add_co_u32_e32 v72, vcc, 0x2000, v72
	v_addc_co_u32_e32 v73, vcc, 0, v73, vcc
	global_load_dwordx4 v[24:27], v[72:73], off
	v_add_co_u32_e32 v72, vcc, 0x2000, v72
	v_addc_co_u32_e32 v73, vcc, 0, v73, vcc
	global_load_dwordx4 v[28:31], v[72:73], off
	v_add_co_u32_e32 v72, vcc, 0x2000, v72
	v_addc_co_u32_e32 v73, vcc, 0, v73, vcc
	global_load_dwordx4 v[32:35], v[72:73], off
	v_add_co_u32_e32 v72, vcc, 0x2000, v72
	v_addc_co_u32_e32 v73, vcc, 0, v73, vcc
	global_load_dwordx4 v[36:39], v[72:73], off
	v_add_co_u32_e32 v72, vcc, 0x2000, v72
	v_addc_co_u32_e32 v73, vcc, 0, v73, vcc
	global_load_dwordx4 v[40:43], v[72:73], off
	v_add_co_u32_e32 v72, vcc, 0x2000, v72
	v_addc_co_u32_e32 v73, vcc, 0, v73, vcc
	global_load_dwordx4 v[44:47], v[72:73], off
	v_add_co_u32_e32 v72, vcc, 0x2000, v72
	v_addc_co_u32_e32 v73, vcc, 0, v73, vcc
	global_load_dwordx4 v[48:51], v[72:73], off
	v_add_co_u32_e32 v72, vcc, 0x2000, v72
	v_addc_co_u32_e32 v73, vcc, 0, v73, vcc
	global_load_dwordx4 v[52:55], v[72:73], off
	v_add_co_u32_e32 v72, vcc, 0x2000, v72
	v_addc_co_u32_e32 v73, vcc, 0, v73, vcc
	global_load_dwordx4 v[56:59], v[72:73], off
	v_add_co_u32_e32 v72, vcc, 0x2000, v72
	v_addc_co_u32_e32 v73, vcc, 0, v73, vcc
	global_load_dwordx4 v[60:63], v[72:73], off
	v_add_co_u32_e32 v72, vcc, 0x2000, v72
	v_addc_co_u32_e32 v73, vcc, 0, v73, vcc
	global_load_dwordx4 v[64:67], v[72:73], off
	v_add_co_u32_e32 v72, vcc, 0x2000, v72
	v_addc_co_u32_e32 v73, vcc, 0, v73, vcc
	global_load_dwordx4 v[68:71], v[72:73], off
	s_waitcnt vmcnt(0)
	ds_write_b128 v74, v[8:11]
	ds_write_b128 v74, v[12:15] offset:8448
	ds_write_b128 v74, v[16:19] offset:16896
	ds_write_b128 v74, v[20:23] offset:25344
	ds_write_b128 v74, v[24:27] offset:33792
	ds_write_b128 v74, v[28:31] offset:42240
	ds_write_b128 v74, v[32:35] offset:50688
	ds_write_b128 v74, v[36:39] offset:59136
	ds_write_b128 v75, v[40:43]
	ds_write_b128 v75, v[44:47] offset:8448
	ds_write_b128 v75, v[48:51] offset:16896
	ds_write_b128 v75, v[52:55] offset:25344
	ds_write_b128 v75, v[56:59] offset:33792
	ds_write_b128 v75, v[60:63] offset:42240
	ds_write_b128 v75, v[64:67] offset:50688
	ds_write_b128 v75, v[68:71] offset:59136
